# speedup vs baseline: 1.0157x; 1.0034x over previous
; template <int K, int EPI, bool MIX = false>
; __device__ __forceinline__ void gemm_phase(const Params& p, const u16* __restrict__ A, const u16* __restrict__ Bt,
;                            const float* __restrict__ rs_in, float* __restrict__ ssq_out, float alpha, bool rev = false) {
;     ...
;     if constexpr (EPI == EPI_SWIGLU) {
; #pragma unroll
;       for (int ai = 0; ai < 2; ++ai)
; #pragma unroll
;         for (int m = 0; m < 4; ++m) {
;           int row = brow + ai * 128 + wr * 64 + m * 16 + fr_e;
;           const float rs = rsqrtf(rsq[ai][m] * (1.f / DM) + 1e-6f);
;           const float c1 = rs * -1.4426950408889634f, rs2 = rs * rs;
;           u16* orow = p.Bbuf + blk_off(row, cpn * 128 + wc * 32, DFF) + wn16;
;           uint2 o2[2];
; #pragma unroll
;           for (int n = 0; n < 2; ++n) {
;             f32x4 g = acc[ai][0][m][n], u = acc[ai][1][m][n];
;             float h[4];
; #pragma unroll
;             for (int j = 0; j < 4; ++j) h[j] = (g[j] * u[j]) * (rs2 * __builtin_amdgcn_rcpf(1.f + __builtin_amdgcn_exp2f(g[j] * c1)));
;             o2[n].x = pk2(h[0], h[1]); o2[n].y = pk2(h[2], h[3]);
;           }
;           *(uint4*)orow = widen_pair(o2[0], o2[1]);
;         }
.LBB0_110:
	v_mov_b32_e32 v129, v220
	v_pk_mul_f32 v[126:127], v[122:123], v[126:127]
	v_lshrrev_b32_e32 v130, 1, v129
	v_ashrrev_i32_e32 v128, 1, v129
	v_and_b32_e32 v130, 8, v130
	v_and_or_b32 v128, v128, -16, v130
	s_waitcnt vmcnt(6)
	v_fmamk_f32 v130, v210, 0x3a000000, v234
	v_cmp_gt_f32_e32 vcc, s78, v130
	v_mul_f32_e32 v132, 0x4b800000, v130
	v_and_or_b32 v131, v129, 15, s50
	v_cndmask_b32_e32 v130, v130, v132, vcc
	v_rsq_f32_e32 v130, v130
	v_lshlrev_b32_e32 v131, 7, v131
	v_and_b32_e32 v210, 0x2780, v131
	v_pk_mul_f32 v[118:119], v[114:115], v[118:119]
	v_mul_f32_e32 v132, 0x45800000, v130
	v_cndmask_b32_e32 v130, v130, v132, vcc
	v_mul_f32_e32 v136, 0xbfb8aa3b, v130
	v_mul_f32_e32 v131, v136, v120
	v_exp_f32_e32 v131, v131
	v_mul_f32_e32 v122, v136, v122
	v_mul_f32_e32 v123, v136, v123
	v_exp_f32_e32 v122, v122
	v_add_f32_e32 v131, 1.0, v131
	v_rcp_f32_e32 v134, v131
	v_mul_f32_e32 v131, v136, v121
	v_exp_f32_e32 v131, v131
	v_exp_f32_e32 v123, v123
	v_add_f32_e32 v122, 1.0, v122
	v_rcp_f32_e32 v122, v122
	v_add_f32_e32 v131, 1.0, v131
	v_add_f32_e32 v123, 1.0, v123
	v_rcp_f32_e32 v135, v131
	v_rcp_f32_e32 v123, v123
	v_mul_f32_e32 v130, v130, v130
	v_pk_mul_f32 v[120:121], v[120:121], v[124:125]
	v_pk_mul_f32 v[124:125], v[130:131], v[134:135] op_sel_hi:[0,1]
	v_pk_mul_f32 v[122:123], v[130:131], v[122:123] op_sel_hi:[0,1]
	v_pk_mul_f32 v[120:121], v[124:125], v[120:121]
	v_pk_mul_f32 v[122:123], v[122:123], v[126:127]
	v_cvt_pk_bf16_f32 v120, v120, v121
	v_cvt_pk_bf16_f32 v121, v122, v123
	v_mul_f32_e32 v122, v136, v112
	v_mul_f32_e32 v123, v136, v113
	v_exp_f32_e32 v122, v122
	v_exp_f32_e32 v123, v123
	v_pk_mul_f32 v[112:113], v[112:113], v[116:117]
	v_mul_f32_e32 v114, v136, v114
	v_add_f32_e32 v122, 1.0, v122
	v_add_f32_e32 v123, 1.0, v123
	v_rcp_f32_e32 v122, v122
	v_rcp_f32_e32 v123, v123
	v_mul_f32_e32 v115, v136, v115
	v_exp_f32_e32 v114, v114
	v_exp_f32_e32 v115, v115
	v_pk_mul_f32 v[116:117], v[130:131], v[122:123] op_sel_hi:[0,1]
	v_pk_mul_f32 v[112:113], v[116:117], v[112:113]
	v_fmamk_f32 v116, v241, 0x3a000000, v234
	v_cmp_gt_f32_e32 vcc, s78, v116
	v_mul_f32_e32 v117, 0x4b800000, v116
	v_add_f32_e32 v114, 1.0, v114
	v_cndmask_b32_e32 v116, v116, v117, vcc
	v_rsq_f32_e32 v116, v116
	v_add_f32_e32 v115, 1.0, v115
	v_rcp_f32_e32 v114, v114
	v_rcp_f32_e32 v115, v115
	v_mul_f32_e32 v117, 0x45800000, v116
	v_cndmask_b32_e32 v116, v116, v117, vcc
	v_mul_f32_e32 v117, 0xbfb8aa3b, v116
	v_pk_mul_f32 v[114:115], v[130:131], v[114:115] op_sel_hi:[0,1]
	v_pk_mul_f32 v[114:115], v[114:115], v[118:119]
	v_mul_f32_e32 v118, v117, v104
	v_mul_f32_e32 v119, v117, v105
	v_pk_mul_f32 v[110:111], v[106:107], v[110:111]
	v_mul_f32_e32 v106, v117, v106
	v_mul_f32_e32 v107, v117, v107
	v_exp_f32_e32 v118, v118
	v_exp_f32_e32 v119, v119
	v_exp_f32_e32 v106, v106
	v_exp_f32_e32 v107, v107
	v_add_f32_e32 v118, 1.0, v118
	v_add_f32_e32 v119, 1.0, v119
	v_add_f32_e32 v106, 1.0, v106
	v_add_f32_e32 v107, 1.0, v107
	v_rcp_f32_e32 v118, v118
	v_rcp_f32_e32 v119, v119
	v_rcp_f32_e32 v106, v106
	v_rcp_f32_e32 v107, v107
	v_mul_f32_e32 v116, v116, v116
	v_pk_mul_f32 v[104:105], v[104:105], v[108:109]
	v_pk_mul_f32 v[108:109], v[116:117], v[118:119] op_sel_hi:[0,1]
	v_pk_mul_f32 v[106:107], v[116:117], v[106:107] op_sel_hi:[0,1]
	v_pk_mul_f32 v[104:105], v[108:109], v[104:105]
	v_pk_mul_f32 v[106:107], v[106:107], v[110:111]
	v_cvt_pk_bf16_f32 v104, v104, v105
	v_cvt_pk_bf16_f32 v105, v106, v107
	v_mul_f32_e32 v106, v117, v96
	v_mul_f32_e32 v107, v117, v97
	v_exp_f32_e32 v106, v106
	v_exp_f32_e32 v107, v107
	v_pk_mul_f32 v[102:103], v[98:99], v[102:103]
	v_mul_f32_e32 v98, v117, v98
	v_add_f32_e32 v106, 1.0, v106
	v_add_f32_e32 v107, 1.0, v107
	v_rcp_f32_e32 v106, v106
	v_rcp_f32_e32 v107, v107
	v_mul_f32_e32 v99, v117, v99
	v_pk_mul_f32 v[96:97], v[96:97], v[100:101]
	v_exp_f32_e32 v98, v98
	v_pk_mul_f32 v[100:101], v[116:117], v[106:107] op_sel_hi:[0,1]
	v_exp_f32_e32 v99, v99
	v_pk_mul_f32 v[96:97], v[100:101], v[96:97]
	v_add_f32_e32 v98, 1.0, v98
	v_cvt_pk_bf16_f32 v106, v96, v97
	v_fmamk_f32 v96, v240, 0x3a000000, v234
	v_cmp_gt_f32_e32 vcc, s78, v96
	v_mul_f32_e32 v97, 0x4b800000, v96
	v_add_f32_e32 v99, 1.0, v99
	v_cndmask_b32_e32 v96, v96, v97, vcc
	v_rcp_f32_e32 v98, v98
	v_rcp_f32_e32 v99, v99
	v_rsq_f32_e32 v96, v96
	v_pk_mul_f32 v[94:95], v[90:91], v[94:95]
	v_pk_mul_f32 v[86:87], v[82:83], v[86:87]
	v_pk_mul_f32 v[98:99], v[116:117], v[98:99] op_sel_hi:[0,1]
	v_mul_f32_e32 v97, 0x45800000, v96
	v_pk_mul_f32 v[98:99], v[98:99], v[102:103]
	v_cndmask_b32_e32 v96, v96, v97, vcc
	v_cvt_pk_bf16_f32 v107, v98, v99
	v_mul_f32_e32 v99, 0xbfb8aa3b, v96
	v_mul_f32_e32 v102, v99, v88
	v_mul_f32_e32 v103, v99, v89
	v_mul_f32_e32 v90, v99, v90
	v_mul_f32_e32 v91, v99, v91
	v_exp_f32_e32 v102, v102
	v_exp_f32_e32 v103, v103
	v_exp_f32_e32 v90, v90
	v_exp_f32_e32 v91, v91
	v_add_f32_e32 v102, 1.0, v102
	v_add_f32_e32 v103, 1.0, v103
	v_add_f32_e32 v90, 1.0, v90
	v_add_f32_e32 v91, 1.0, v91
	v_rcp_f32_e32 v102, v102
	v_rcp_f32_e32 v103, v103
	v_rcp_f32_e32 v90, v90
	v_rcp_f32_e32 v91, v91
	v_mul_f32_e32 v98, v96, v96
	v_pk_mul_f32 v[88:89], v[88:89], v[92:93]
	v_pk_mul_f32 v[92:93], v[98:99], v[102:103] op_sel_hi:[0,1]
	v_pk_mul_f32 v[90:91], v[98:99], v[90:91] op_sel_hi:[0,1]
	v_pk_mul_f32 v[88:89], v[92:93], v[88:89]
	v_pk_mul_f32 v[90:91], v[90:91], v[94:95]
	v_cvt_pk_bf16_f32 v88, v88, v89
	v_cvt_pk_bf16_f32 v89, v90, v91
	v_mul_f32_e32 v90, v99, v80
	v_mul_f32_e32 v91, v99, v81
	v_mul_f32_e32 v82, v99, v82
	v_mul_f32_e32 v83, v99, v83
	s_lshl_b32 s38, s80, 7
	v_exp_f32_e32 v90, v90
	v_exp_f32_e32 v91, v91
	v_exp_f32_e32 v82, v82
; __device__ __forceinline__ size_t blk_off(int r, int c, int K) {
;   return ((size_t)(r >> 7) * (K >> 6) + (c >> 6)) * 8192 + (r & 127) * 64 + (c & 63);
; }
; template <int K, int EPI, bool MIX = false>
; __device__ __forceinline__ void gemm_phase(const Params& p, const u16* __restrict__ A, const u16* __restrict__ Bt,
;                            const float* __restrict__ rs_in, float* __restrict__ ssq_out, float alpha, bool rev = false) {
;     ...
;     if constexpr (EPI == EPI_SWIGLU) {
; #pragma unroll
;       for (int ai = 0; ai < 2; ++ai)
; #pragma unroll
;         for (int m = 0; m < 4; ++m) {
;           int row = brow + ai * 128 + wr * 64 + m * 16 + fr_e;
;           const float rs = rsqrtf(rsq[ai][m] * (1.f / DM) + 1e-6f);
;           const float c1 = rs * -1.4426950408889634f, rs2 = rs * rs;
;           u16* orow = p.Bbuf + blk_off(row, cpn * 128 + wc * 32, DFF) + wn16;
;           uint2 o2[2];
; #pragma unroll
;           for (int n = 0; n < 2; ++n) {
;             f32x4 g = acc[ai][0][m][n], u = acc[ai][1][m][n];
;             float h[4];
; #pragma unroll
;             for (int j = 0; j < 4; ++j) h[j] = (g[j] * u[j]) * (rs2 * __builtin_amdgcn_rcpf(1.f + __builtin_amdgcn_exp2f(g[j] * c1)));
;             o2[n].x = pk2(h[0], h[1]); o2[n].y = pk2(h[2], h[3]);
;           }
;           *(uint4*)orow = widen_pair(o2[0], o2[1]);
;         }
	v_exp_f32_e32 v83, v83
	s_or_b32 s38, s38, s51
	s_ashr_i32 s80, s38, 6
	s_ashr_i32 s38, s41, 7
	s_mulk_i32 s38, 0x58
	s_ashr_i32 s81, s80, 31
	s_ashr_i32 s39, s38, 31
	v_add_f32_e32 v90, 1.0, v90
	v_add_f32_e32 v91, 1.0, v91
	v_add_f32_e32 v82, 1.0, v82
	v_add_f32_e32 v83, 1.0, v83
	s_add_u32 s38, s38, s80
	v_rcp_f32_e32 v90, v90
	v_rcp_f32_e32 v91, v91
	v_rcp_f32_e32 v82, v82
	v_rcp_f32_e32 v83, v83
	s_addc_u32 s39, s39, s81
	s_lshl_b64 s[38:39], s[38:39], 14
	s_add_u32 s38, s92, s38
	s_addc_u32 s39, s93, s39
	v_or_b32_e32 v96, 0x1000, v210
	v_mov_b32_e32 v97, v211
	v_pk_mul_f32 v[80:81], v[80:81], v[84:85]
	v_pk_mul_f32 v[84:85], v[98:99], v[90:91] op_sel_hi:[0,1]
	v_pk_mul_f32 v[82:83], v[98:99], v[82:83] op_sel_hi:[0,1]
	v_ashrrev_i32_e32 v129, 31, v128
	v_lshl_add_u64 v[100:101], s[38:39], 0, v[96:97]
	v_pk_mul_f32 v[80:81], v[84:85], v[80:81]
	v_pk_mul_f32 v[82:83], v[82:83], v[86:87]
	v_cvt_pk_bf16_f32 v122, v112, v113
	v_lshlrev_b64 v[112:113], 1, v[128:129]
	v_lshl_add_u64 v[100:101], v[100:101], 0, s[20:21]
	v_cvt_pk_bf16_f32 v90, v80, v81
	v_cvt_pk_bf16_f32 v91, v82, v83
	v_lshl_add_u64 v[80:81], v[100:101], 0, v[112:113]
	v_permlane32_swap_b32_e32 v88, v90
	v_permlane32_swap_b32_e32 v89, v91
	global_store_dwordx4 v[80:81], v[88:91], off sc0 sc1
	v_fmamk_f32 v80, v239, 0x3a000000, v234
	v_cmp_gt_f32_e32 vcc, s78, v80
	v_mul_f32_e32 v81, 0x4b800000, v80
	v_pk_mul_f32 v[78:79], v[74:75], v[78:79]
	v_cndmask_b32_e32 v80, v80, v81, vcc
	v_rsq_f32_e32 v80, v80
	v_pk_mul_f32 v[70:71], v[66:67], v[70:71]
	v_pk_mul_f32 v[62:63], v[58:59], v[62:63]
	v_pk_mul_f32 v[54:55], v[50:51], v[54:55]
	v_mul_f32_e32 v81, 0x45800000, v80
	v_cndmask_b32_e32 v80, v80, v81, vcc
	v_mul_f32_e32 v83, 0xbfb8aa3b, v80
	v_mul_f32_e32 v86, v83, v72
	v_mul_f32_e32 v87, v83, v73
	v_mul_f32_e32 v74, v83, v74
	v_mul_f32_e32 v75, v83, v75
	v_exp_f32_e32 v86, v86
	v_exp_f32_e32 v87, v87
	v_exp_f32_e32 v74, v74
	v_exp_f32_e32 v75, v75
	v_add_f32_e32 v86, 1.0, v86
	v_add_f32_e32 v87, 1.0, v87
	v_add_f32_e32 v74, 1.0, v74
	v_add_f32_e32 v75, 1.0, v75
	v_rcp_f32_e32 v86, v86
	v_rcp_f32_e32 v87, v87
	v_rcp_f32_e32 v74, v74
	v_rcp_f32_e32 v75, v75
	v_mul_f32_e32 v82, v80, v80
	v_pk_mul_f32 v[72:73], v[72:73], v[76:77]
	v_pk_mul_f32 v[76:77], v[82:83], v[86:87] op_sel_hi:[0,1]
	v_pk_mul_f32 v[74:75], v[82:83], v[74:75] op_sel_hi:[0,1]
	v_pk_mul_f32 v[72:73], v[76:77], v[72:73]
	v_pk_mul_f32 v[74:75], v[74:75], v[78:79]
	v_cvt_pk_bf16_f32 v72, v72, v73
	v_cvt_pk_bf16_f32 v73, v74, v75
	v_mul_f32_e32 v74, v83, v64
	v_mul_f32_e32 v75, v83, v65
	v_mul_f32_e32 v66, v83, v66
	v_mul_f32_e32 v67, v83, v67
	v_exp_f32_e32 v74, v74
	v_exp_f32_e32 v75, v75
	v_exp_f32_e32 v66, v66
	v_exp_f32_e32 v67, v67
	v_add_f32_e32 v74, 1.0, v74
	v_add_f32_e32 v75, 1.0, v75
	v_add_f32_e32 v66, 1.0, v66
	v_add_f32_e32 v67, 1.0, v67
	v_rcp_f32_e32 v74, v74
	v_rcp_f32_e32 v75, v75
	v_rcp_f32_e32 v66, v66
	v_rcp_f32_e32 v67, v67
	v_or_b32_e32 v80, 0x1800, v210
	v_mov_b32_e32 v81, v211
	v_pk_mul_f32 v[64:65], v[64:65], v[68:69]
	v_pk_mul_f32 v[68:69], v[82:83], v[74:75] op_sel_hi:[0,1]
	v_pk_mul_f32 v[66:67], v[82:83], v[66:67] op_sel_hi:[0,1]
	v_lshl_add_u64 v[84:85], s[38:39], 0, v[80:81]
	v_pk_mul_f32 v[64:65], v[68:69], v[64:65]
	v_pk_mul_f32 v[66:67], v[66:67], v[70:71]
	v_lshl_add_u64 v[84:85], v[84:85], 0, s[20:21]
	v_cvt_pk_bf16_f32 v74, v64, v65
	v_cvt_pk_bf16_f32 v75, v66, v67
	v_lshl_add_u64 v[64:65], v[84:85], 0, v[112:113]
	v_permlane32_swap_b32_e32 v72, v74
	v_permlane32_swap_b32_e32 v73, v75
	global_store_dwordx4 v[64:65], v[72:75], off sc0 sc1
	v_fmamk_f32 v64, v238, 0x3a000000, v234
	v_cmp_gt_f32_e32 vcc, s78, v64
	v_mul_f32_e32 v65, 0x4b800000, v64
	v_pk_mul_f32 v[46:47], v[42:43], v[46:47]
	v_cndmask_b32_e32 v64, v64, v65, vcc
	v_rsq_f32_e32 v64, v64
	v_pk_mul_f32 v[30:31], v[26:27], v[30:31]
	v_pk_mul_f32 v[38:39], v[34:35], v[38:39]
	v_pk_mul_f32 v[22:23], v[18:19], v[22:23]
	v_mul_f32_e32 v65, 0x45800000, v64
	v_cndmask_b32_e32 v64, v64, v65, vcc
	v_mul_f32_e32 v65, 0xbfb8aa3b, v64
	v_mul_f32_e32 v68, v65, v56
	v_mul_f32_e32 v69, v65, v57
	v_mul_f32_e32 v58, v65, v58
	v_mul_f32_e32 v59, v65, v59
	v_exp_f32_e32 v68, v68
	v_exp_f32_e32 v69, v69
	v_exp_f32_e32 v58, v58
	v_exp_f32_e32 v59, v59
	v_add_f32_e32 v68, 1.0, v68
	v_add_f32_e32 v69, 1.0, v69
	v_add_f32_e32 v58, 1.0, v58
	v_add_f32_e32 v59, 1.0, v59
	v_rcp_f32_e32 v68, v68
	v_rcp_f32_e32 v69, v69
	v_rcp_f32_e32 v58, v58
	v_rcp_f32_e32 v59, v59
	v_mul_f32_e32 v64, v64, v64
	v_pk_mul_f32 v[56:57], v[56:57], v[60:61]
	v_pk_mul_f32 v[60:61], v[64:65], v[68:69] op_sel_hi:[0,1]
	v_pk_mul_f32 v[58:59], v[64:65], v[58:59] op_sel_hi:[0,1]
	v_mul_f32_e32 v50, v65, v50
	v_mul_f32_e32 v51, v65, v51
	v_pk_mul_f32 v[56:57], v[60:61], v[56:57]
	v_pk_mul_f32 v[58:59], v[58:59], v[62:63]
	v_exp_f32_e32 v50, v50
	v_exp_f32_e32 v51, v51
	v_cvt_pk_bf16_f32 v56, v56, v57
	v_cvt_pk_bf16_f32 v57, v58, v59
	v_mul_f32_e32 v58, v65, v48
	v_mul_f32_e32 v59, v65, v49
	v_exp_f32_e32 v58, v58
	v_exp_f32_e32 v59, v59
	v_add_f32_e32 v50, 1.0, v50
	v_add_f32_e32 v51, 1.0, v51
	v_rcp_f32_e32 v50, v50
	v_rcp_f32_e32 v51, v51
	v_add_f32_e32 v58, 1.0, v58
	v_add_f32_e32 v59, 1.0, v59
	v_rcp_f32_e32 v58, v58
	v_rcp_f32_e32 v59, v59
	v_pk_mul_f32 v[50:51], v[64:65], v[50:51] op_sel_hi:[0,1]
	v_pk_mul_f32 v[50:51], v[50:51], v[54:55]
	v_pk_mul_f32 v[48:49], v[48:49], v[52:53]
	v_pk_mul_f32 v[52:53], v[64:65], v[58:59] op_sel_hi:[0,1]
	v_cvt_pk_bf16_f32 v59, v50, v51
	v_fmamk_f32 v50, v237, 0x3a000000, v234
	v_cmp_gt_f32_e32 vcc, s78, v50
	v_mul_f32_e32 v51, 0x4b800000, v50
	v_pk_mul_f32 v[48:49], v[52:53], v[48:49]
	v_cndmask_b32_e32 v50, v50, v51, vcc
; template <int K, int EPI, bool MIX = false>
; __device__ __forceinline__ void gemm_phase(const Params& p, const u16* __restrict__ A, const u16* __restrict__ Bt,
;                            const float* __restrict__ rs_in, float* __restrict__ ssq_out, float alpha, bool rev = false) {
;     ...
;     if constexpr (EPI == EPI_SWIGLU) {
; #pragma unroll
;       for (int ai = 0; ai < 2; ++ai)
; #pragma unroll
;         for (int m = 0; m < 4; ++m) {
;           int row = brow + ai * 128 + wr * 64 + m * 16 + fr_e;
;           const float rs = rsqrtf(rsq[ai][m] * (1.f / DM) + 1e-6f);
;           const float c1 = rs * -1.4426950408889634f, rs2 = rs * rs;
;           u16* orow = p.Bbuf + blk_off(row, cpn * 128 + wc * 32, DFF) + wn16;
;           uint2 o2[2];
; #pragma unroll
;           for (int n = 0; n < 2; ++n) {
;             f32x4 g = acc[ai][0][m][n], u = acc[ai][1][m][n];
;             float h[4];
; #pragma unroll
;             for (int j = 0; j < 4; ++j) h[j] = (g[j] * u[j]) * (rs2 * __builtin_amdgcn_rcpf(1.f + __builtin_amdgcn_exp2f(g[j] * c1)));
;             o2[n].x = pk2(h[0], h[1]); o2[n].y = pk2(h[2], h[3]);
;           }
;           *(uint4*)orow = widen_pair(o2[0], o2[1]);
;         }
	v_rsq_f32_e32 v50, v50
	s_addk_i32 s41, 0x80
	v_lshl_add_u64 v[132:133], s[38:39], 0, v[210:211]
	s_ashr_i32 s38, s41, 7
	v_mul_f32_e32 v51, 0x45800000, v50
	v_cndmask_b32_e32 v50, v50, v51, vcc
	v_mul_f32_e32 v51, 0xbfb8aa3b, v50
	v_mul_f32_e32 v52, v51, v40
	v_mul_f32_e32 v53, v51, v41
	v_mul_f32_e32 v42, v51, v42
	v_mul_f32_e32 v43, v51, v43
	v_exp_f32_e32 v52, v52
	v_exp_f32_e32 v53, v53
	v_exp_f32_e32 v42, v42
	v_exp_f32_e32 v43, v43
	v_add_f32_e32 v52, 1.0, v52
	v_add_f32_e32 v53, 1.0, v53
	v_add_f32_e32 v42, 1.0, v42
	v_add_f32_e32 v43, 1.0, v43
	v_rcp_f32_e32 v52, v52
	v_rcp_f32_e32 v53, v53
	v_rcp_f32_e32 v42, v42
	v_rcp_f32_e32 v43, v43
	v_mul_f32_e32 v50, v50, v50
	v_pk_mul_f32 v[40:41], v[40:41], v[44:45]
	v_pk_mul_f32 v[44:45], v[50:51], v[52:53] op_sel_hi:[0,1]
	v_pk_mul_f32 v[42:43], v[50:51], v[42:43] op_sel_hi:[0,1]
	v_pk_mul_f32 v[40:41], v[44:45], v[40:41]
	v_pk_mul_f32 v[42:43], v[42:43], v[46:47]
	v_cvt_pk_bf16_f32 v40, v40, v41
	v_cvt_pk_bf16_f32 v41, v42, v43
	v_mul_f32_e32 v42, v51, v32
	v_mul_f32_e32 v43, v51, v33
	v_exp_f32_e32 v42, v42
	v_exp_f32_e32 v43, v43
	v_pk_mul_f32 v[32:33], v[32:33], v[36:37]
	v_mul_f32_e32 v34, v51, v34
	v_add_f32_e32 v42, 1.0, v42
	v_add_f32_e32 v43, 1.0, v43
	v_rcp_f32_e32 v42, v42
	v_rcp_f32_e32 v43, v43
	v_mul_f32_e32 v35, v51, v35
	v_exp_f32_e32 v34, v34
	v_exp_f32_e32 v35, v35
	v_pk_mul_f32 v[36:37], v[50:51], v[42:43] op_sel_hi:[0,1]
	v_pk_mul_f32 v[32:33], v[36:37], v[32:33]
	s_mulk_i32 s38, 0x58
	v_cvt_pk_bf16_f32 v42, v32, v33
	v_fmamk_f32 v32, v236, 0x3a000000, v234
	v_cmp_gt_f32_e32 vcc, s78, v32
	v_mul_f32_e32 v33, 0x4b800000, v32
	v_add_f32_e32 v34, 1.0, v34
	v_cndmask_b32_e32 v32, v32, v33, vcc
	v_rsq_f32_e32 v32, v32
	v_add_f32_e32 v35, 1.0, v35
	s_ashr_i32 s39, s38, 31
	v_rcp_f32_e32 v34, v34
	v_mul_f32_e32 v33, 0x45800000, v32
	v_cndmask_b32_e32 v32, v32, v33, vcc
	v_mul_f32_e32 v33, 0xbfb8aa3b, v32
	v_mul_f32_e32 v36, v33, v24
	v_mul_f32_e32 v37, v33, v25
	v_mul_f32_e32 v26, v33, v26
	v_mul_f32_e32 v27, v33, v27
	v_exp_f32_e32 v36, v36
	v_exp_f32_e32 v37, v37
	v_exp_f32_e32 v26, v26
	v_exp_f32_e32 v27, v27
	v_add_f32_e32 v36, 1.0, v36
	v_add_f32_e32 v37, 1.0, v37
	v_add_f32_e32 v26, 1.0, v26
	v_add_f32_e32 v27, 1.0, v27
	v_rcp_f32_e32 v36, v36
	v_rcp_f32_e32 v37, v37
	v_rcp_f32_e32 v26, v26
	v_rcp_f32_e32 v27, v27
	v_mul_f32_e32 v32, v32, v32
	v_pk_mul_f32 v[24:25], v[24:25], v[28:29]
	v_pk_mul_f32 v[28:29], v[32:33], v[36:37] op_sel_hi:[0,1]
	v_pk_mul_f32 v[26:27], v[32:33], v[26:27] op_sel_hi:[0,1]
	v_pk_mul_f32 v[24:25], v[28:29], v[24:25]
	v_pk_mul_f32 v[26:27], v[26:27], v[30:31]
	v_cvt_pk_bf16_f32 v24, v24, v25
	v_cvt_pk_bf16_f32 v25, v26, v27
	v_mul_f32_e32 v26, v33, v16
	v_mul_f32_e32 v27, v33, v17
	v_mul_f32_e32 v18, v33, v18
	v_mul_f32_e32 v19, v33, v19
	v_exp_f32_e32 v26, v26
	v_exp_f32_e32 v27, v27
	v_exp_f32_e32 v18, v18
	v_exp_f32_e32 v19, v19
	v_rcp_f32_e32 v35, v35
	v_add_f32_e32 v26, 1.0, v26
	v_add_f32_e32 v27, 1.0, v27
	v_add_f32_e32 v18, 1.0, v18
	v_add_f32_e32 v19, 1.0, v19
	s_add_u32 s38, s38, s80
	v_rcp_f32_e32 v26, v26
	v_rcp_f32_e32 v27, v27
	v_rcp_f32_e32 v18, v18
	v_rcp_f32_e32 v19, v19
	s_addc_u32 s39, s39, s81
	s_lshl_b64 s[38:39], s[38:39], 14
	s_add_u32 s38, s92, s38
	v_pk_mul_f32 v[34:35], v[50:51], v[34:35] op_sel_hi:[0,1]
	s_addc_u32 s39, s93, s39
	v_pk_mul_f32 v[34:35], v[34:35], v[38:39]
	v_pk_mul_f32 v[16:17], v[16:17], v[20:21]
	v_pk_mul_f32 v[20:21], v[32:33], v[26:27] op_sel_hi:[0,1]
	v_pk_mul_f32 v[18:19], v[32:33], v[18:19] op_sel_hi:[0,1]
	v_cvt_pk_bf16_f32 v43, v34, v35
	v_lshl_add_u64 v[34:35], s[38:39], 0, v[96:97]
	v_pk_mul_f32 v[16:17], v[20:21], v[16:17]
	v_pk_mul_f32 v[18:19], v[18:19], v[22:23]
	v_lshl_add_u64 v[34:35], v[34:35], 0, s[20:21]
	v_cvt_pk_bf16_f32 v26, v16, v17
	v_cvt_pk_bf16_f32 v27, v18, v19
	v_lshl_add_u64 v[16:17], v[34:35], 0, v[112:113]
	v_permlane32_swap_b32_e32 v24, v26
	v_permlane32_swap_b32_e32 v25, v27
	global_store_dwordx4 v[16:17], v[24:27], off sc0 sc1
	v_fmamk_f32 v16, v235, 0x3a000000, v234
	v_cmp_gt_f32_e32 vcc, s78, v16
	v_mul_f32_e32 v17, 0x4b800000, v16
	v_pk_mul_f32 v[14:15], v[10:11], v[14:15]
	v_cndmask_b32_e32 v16, v16, v17, vcc
	v_rsq_f32_e32 v16, v16
	v_pk_mul_f32 v[6:7], v[2:3], v[6:7]
	v_lshl_add_u64 v[66:67], s[38:39], 0, v[210:211]
	v_lshl_add_u64 v[18:19], s[38:39], 0, v[80:81]
	v_mul_f32_e32 v17, 0x45800000, v16
	v_cndmask_b32_e32 v16, v16, v17, vcc
	v_mul_f32_e32 v17, 0xbfb8aa3b, v16
	v_mul_f32_e32 v20, v17, v8
	v_mul_f32_e32 v21, v17, v9
	v_mul_f32_e32 v10, v17, v10
	v_mul_f32_e32 v11, v17, v11
	v_exp_f32_e32 v20, v20
	v_exp_f32_e32 v21, v21
	v_exp_f32_e32 v10, v10
	v_exp_f32_e32 v11, v11
	v_add_f32_e32 v20, 1.0, v20
	v_add_f32_e32 v21, 1.0, v21
	v_add_f32_e32 v10, 1.0, v10
	v_add_f32_e32 v11, 1.0, v11
	v_rcp_f32_e32 v20, v20
	v_rcp_f32_e32 v21, v21
	v_rcp_f32_e32 v10, v10
	v_rcp_f32_e32 v11, v11
	v_mul_f32_e32 v16, v16, v16
	v_pk_mul_f32 v[8:9], v[8:9], v[12:13]
	v_pk_mul_f32 v[12:13], v[16:17], v[20:21] op_sel_hi:[0,1]
	v_pk_mul_f32 v[10:11], v[16:17], v[10:11] op_sel_hi:[0,1]
	v_pk_mul_f32 v[8:9], v[12:13], v[8:9]
	v_pk_mul_f32 v[10:11], v[10:11], v[14:15]
	v_cvt_pk_bf16_f32 v8, v8, v9
	v_cvt_pk_bf16_f32 v9, v10, v11
	v_mul_f32_e32 v10, v17, v0
	v_mul_f32_e32 v11, v17, v1
	v_mul_f32_e32 v2, v17, v2
	v_mul_f32_e32 v3, v17, v3
	v_exp_f32_e32 v10, v10
	v_exp_f32_e32 v11, v11
	v_exp_f32_e32 v2, v2
	v_exp_f32_e32 v3, v3
	v_add_f32_e32 v10, 1.0, v10
	v_add_f32_e32 v11, 1.0, v11
	v_add_f32_e32 v2, 1.0, v2
	v_add_f32_e32 v3, 1.0, v3
	v_rcp_f32_e32 v10, v10
	v_rcp_f32_e32 v11, v11
	v_rcp_f32_e32 v2, v2
	v_rcp_f32_e32 v3, v3
	v_pk_mul_f32 v[0:1], v[0:1], v[4:5]
	v_pk_mul_f32 v[4:5], v[16:17], v[10:11] op_sel_hi:[0,1]
	v_pk_mul_f32 v[0:1], v[4:5], v[0:1]
	v_pk_mul_f32 v[2:3], v[16:17], v[2:3] op_sel_hi:[0,1]
	v_pk_mul_f32 v[2:3], v[2:3], v[6:7]
	v_lshl_add_u64 v[132:133], v[132:133], 0, s[20:21]
	v_cvt_pk_bf16_f32 v123, v114, v115
	v_lshl_add_u64 v[66:67], v[66:67], 0, s[20:21]
	v_cvt_pk_bf16_f32 v58, v48, v49
	v_lshl_add_u64 v[18:19], v[18:19], 0, s[20:21]
	v_cvt_pk_bf16_f32 v10, v0, v1
	v_cvt_pk_bf16_f32 v11, v2, v3
	v_lshl_add_u64 v[114:115], v[132:133], 0, v[112:113]
	v_permlane32_swap_b32_e32 v120, v122
	v_permlane32_swap_b32_e32 v121, v123
	v_permlane32_swap_b32_e32 v104, v106
	v_permlane32_swap_b32_e32 v105, v107
	v_lshl_add_u64 v[48:49], v[66:67], 0, v[112:113]
	v_permlane32_swap_b32_e32 v56, v58
	v_permlane32_swap_b32_e32 v57, v59
	v_permlane32_swap_b32_e32 v40, v42
	v_permlane32_swap_b32_e32 v41, v43
	v_lshl_add_u64 v[0:1], v[18:19], 0, v[112:113]
	v_permlane32_swap_b32_e32 v8, v10
	v_permlane32_swap_b32_e32 v9, v11
	s_mov_b64 s[38:39], -1
	s_and_b64 vcc, exec, s[4:5]
	global_store_dwordx4 v[114:115], v[120:123], off sc0 sc1
	global_store_dwordx4 v[114:115], v[104:107], off offset:2048 sc0 sc1
	global_store_dwordx4 v[48:49], v[56:59], off sc0 sc1
	global_store_dwordx4 v[48:49], v[40:43], off offset:2048 sc0 sc1
	global_store_dwordx4 v[0:1], v[8:11], off sc0 sc1
	s_cbranch_vccnz .LBB0_87
	s_mov_b64 s[38:39], 0
	s_branch .LBB0_87

; template <int K, int EPI, bool MIX = false>
; __device__ __forceinline__ void gemm_phase(const Params& p, const u16* __restrict__ A, const u16* __restrict__ Bt,
;                            const float* __restrict__ rs_in, float* __restrict__ ssq_out, float alpha, bool rev = false) {
;     ...
;     if constexpr (EPI == EPI_SWIGLU) {
; #pragma unroll
;       for (int ai = 0; ai < 2; ++ai)
; #pragma unroll
;         for (int m = 0; m < 4; ++m) {
;           int row = brow + ai * 128 + wr * 64 + m * 16 + fr_e;
;           const float rs = rsqrtf(rsq[ai][m] * (1.f / DM) + 1e-6f);
;           const float c1 = rs * -1.4426950408889634f, rs2 = rs * rs;
;           u16* orow = p.Bbuf + blk_off(row, cpn * 128 + wc * 32, DFF) + wn16;
;           uint2 o2[2];
; #pragma unroll
;           for (int n = 0; n < 2; ++n) {
;             f32x4 g = acc[ai][0][m][n], u = acc[ai][1][m][n];
;             float h[4];
; #pragma unroll
;             for (int j = 0; j < 4; ++j) h[j] = (g[j] * u[j]) * (rs2 * __builtin_amdgcn_rcpf(1.f + __builtin_amdgcn_exp2f(g[j] * c1)));
;             o2[n].x = pk2(h[0], h[1]); o2[n].y = pk2(h[2], h[3]);
;           }
;           *(uint4*)orow = widen_pair(o2[0], o2[1]);
;         }
.LBB0_444:
	v_mov_b32_e32 v129, v222
	v_pk_mul_f32 v[118:119], v[126:127], v[118:119]
	v_lshrrev_b32_e32 v130, 1, v129
	v_ashrrev_i32_e32 v128, 1, v129
	v_and_b32_e32 v130, 8, v130
	v_and_or_b32 v128, v128, -16, v130
	s_waitcnt vmcnt(6)
	v_fmamk_f32 v130, v214, 0x3a000000, v236
	v_mul_f32_e32 v132, 0x4b800000, v130
	v_cmp_gt_f32_e32 vcc, s74, v130
	v_and_or_b32 v131, v129, 15, s70
	v_lshlrev_b32_e32 v131, 7, v131
	v_cndmask_b32_e32 v130, v130, v132, vcc
	v_rsq_f32_e32 v130, v130
	v_and_b32_e32 v214, 0x2780, v131
	v_pk_mul_f32 v[116:117], v[124:125], v[116:117]
	s_lshl_b32 s52, s76, 7
	v_mul_f32_e32 v132, 0x45800000, v130
	v_cndmask_b32_e32 v130, v130, v132, vcc
	v_mul_f32_e32 v136, 0xbfb8aa3b, v130
	v_mul_f32_e32 v131, v136, v124
	v_exp_f32_e32 v131, v131
	v_mul_f32_e32 v134, v136, v125
	v_exp_f32_e32 v135, v134
	v_mul_f32_e32 v137, v136, v127
	v_add_f32_e32 v131, 1.0, v131
	v_rcp_f32_e32 v134, v131
	v_add_f32_e32 v131, 1.0, v135
	v_rcp_f32_e32 v135, v131
	v_mul_f32_e32 v131, v136, v126
	v_exp_f32_e32 v131, v131
	v_exp_f32_e32 v137, v137
	v_mul_f32_e32 v130, v130, v130
	s_or_b32 s52, s52, s71
	v_add_f32_e32 v126, 1.0, v131
	v_add_f32_e32 v127, 1.0, v137
	v_rcp_f32_e32 v126, v126
	v_rcp_f32_e32 v127, v127
	v_pk_mul_f32 v[124:125], v[130:131], v[134:135] op_sel_hi:[0,1]
	v_pk_mul_f32 v[116:117], v[124:125], v[116:117]
	s_ashr_i32 s76, s52, 6
	v_pk_mul_f32 v[124:125], v[130:131], v[126:127] op_sel_hi:[0,1]
	v_cvt_pk_bf16_f32 v116, v116, v117
	v_mul_f32_e32 v117, v136, v120
	v_pk_mul_f32 v[118:119], v[124:125], v[118:119]
	v_exp_f32_e32 v124, v117
	v_mul_f32_e32 v117, v136, v121
	v_exp_f32_e32 v125, v117
	v_cvt_pk_bf16_f32 v117, v118, v119
	v_add_f32_e32 v118, 1.0, v124
	v_mul_f32_e32 v124, v136, v122
	v_add_f32_e32 v119, 1.0, v125
	v_mul_f32_e32 v125, v136, v123
	v_exp_f32_e32 v124, v124
	v_exp_f32_e32 v125, v125
	s_ashr_i32 s52, s59, 7
	s_mulk_i32 s52, 0x58
	s_ashr_i32 s77, s76, 31
	s_ashr_i32 s53, s52, 31
	v_rcp_f32_e32 v118, v118
	v_rcp_f32_e32 v119, v119
	v_pk_mul_f32 v[114:115], v[122:123], v[114:115]
	v_add_f32_e32 v122, 1.0, v124
	v_add_f32_e32 v123, 1.0, v125
	s_add_u32 s52, s52, s76
	v_rcp_f32_e32 v122, v122
	v_rcp_f32_e32 v123, v123
	s_addc_u32 s53, s53, s77
	v_pk_mul_f32 v[112:113], v[120:121], v[112:113]
	v_fmamk_f32 v120, v243, 0x3a000000, v236
	s_lshl_b64 s[52:53], s[52:53], 14
	v_mul_f32_e32 v121, 0x4b800000, v120
	v_cmp_gt_f32_e32 vcc, s74, v120
	s_add_u32 s52, s92, s52
	v_pk_mul_f32 v[118:119], v[130:131], v[118:119] op_sel_hi:[0,1]
	v_cndmask_b32_e32 v120, v120, v121, vcc
	s_addc_u32 s53, s93, s53
	v_pk_mul_f32 v[112:113], v[118:119], v[112:113]
	v_pk_mul_f32 v[118:119], v[130:131], v[122:123] op_sel_hi:[0,1]
	v_rsq_f32_e32 v120, v120
	v_ashrrev_i32_e32 v129, 31, v128
	v_lshl_add_u64 v[132:133], s[52:53], 0, v[214:215]
	v_pk_mul_f32 v[114:115], v[118:119], v[114:115]
	v_lshl_add_u64 v[132:133], v[132:133], 0, s[22:23]
	v_cvt_pk_bf16_f32 v118, v112, v113
	v_cvt_pk_bf16_f32 v119, v114, v115
	v_lshlrev_b64 v[112:113], 1, v[128:129]
	v_lshl_add_u64 v[114:115], v[132:133], 0, v[112:113]
	v_permlane32_swap_b32_e32 v116, v118
	v_permlane32_swap_b32_e32 v117, v119
	global_store_dwordx4 v[114:115], v[116:119], off sc0 sc1
	s_addk_i32 s59, 0x80
	s_nop 0
	v_mul_f32_e32 v116, 0x45800000, v120
	v_cndmask_b32_e32 v116, v120, v116, vcc
	v_mul_f32_e32 v117, 0xbfb8aa3b, v116
	v_mul_f32_e32 v118, v117, v100
	v_mul_f32_e32 v119, v117, v101
	v_exp_f32_e32 v118, v118
	v_exp_f32_e32 v119, v119
	v_mul_f32_e32 v120, v117, v102
	v_mul_f32_e32 v121, v117, v103
	v_exp_f32_e32 v120, v120
	v_exp_f32_e32 v121, v121
	v_add_f32_e32 v118, 1.0, v118
	v_add_f32_e32 v119, 1.0, v119
	v_rcp_f32_e32 v118, v118
	v_rcp_f32_e32 v119, v119
	v_pk_mul_f32 v[102:103], v[102:103], v[110:111]
	v_add_f32_e32 v110, 1.0, v120
	v_add_f32_e32 v111, 1.0, v121
	v_rcp_f32_e32 v110, v110
	v_rcp_f32_e32 v111, v111
	v_mul_f32_e32 v116, v116, v116
	v_pk_mul_f32 v[100:101], v[100:101], v[108:109]
	v_pk_mul_f32 v[108:109], v[116:117], v[118:119] op_sel_hi:[0,1]
	v_pk_mul_f32 v[100:101], v[108:109], v[100:101]
	v_pk_mul_f32 v[108:109], v[116:117], v[110:111] op_sel_hi:[0,1]
	v_cvt_pk_bf16_f32 v100, v100, v101
	v_mul_f32_e32 v101, v117, v96
	v_pk_mul_f32 v[102:103], v[108:109], v[102:103]
	v_exp_f32_e32 v108, v101
	v_mul_f32_e32 v101, v117, v97
	v_exp_f32_e32 v109, v101
	v_cvt_pk_bf16_f32 v101, v102, v103
	v_add_f32_e32 v102, 1.0, v108
	v_mul_f32_e32 v108, v117, v98
	v_add_f32_e32 v103, 1.0, v109
	v_mul_f32_e32 v109, v117, v99
	v_exp_f32_e32 v108, v108
	v_exp_f32_e32 v109, v109
	v_rcp_f32_e32 v102, v102
	v_rcp_f32_e32 v103, v103
	v_pk_mul_f32 v[98:99], v[98:99], v[106:107]
	v_add_f32_e32 v106, 1.0, v108
	v_add_f32_e32 v107, 1.0, v109
	v_rcp_f32_e32 v106, v106
	v_rcp_f32_e32 v107, v107
	v_pk_mul_f32 v[96:97], v[96:97], v[104:105]
	v_pk_mul_f32 v[102:103], v[116:117], v[102:103] op_sel_hi:[0,1]
	v_pk_mul_f32 v[96:97], v[102:103], v[96:97]
	v_pk_mul_f32 v[102:103], v[116:117], v[106:107] op_sel_hi:[0,1]
	v_pk_mul_f32 v[98:99], v[102:103], v[98:99]
	v_cvt_pk_bf16_f32 v102, v96, v97
	v_fmamk_f32 v96, v242, 0x3a000000, v236
	v_mul_f32_e32 v97, 0x4b800000, v96
	v_cmp_gt_f32_e32 vcc, s74, v96
	v_cvt_pk_bf16_f32 v103, v98, v99
	v_permlane32_swap_b32_e32 v100, v102
	v_cndmask_b32_e32 v96, v96, v97, vcc
	v_rsq_f32_e32 v96, v96
	v_permlane32_swap_b32_e32 v101, v103
	global_store_dwordx4 v[114:115], v[100:103], off offset:2048 sc0 sc1
	v_mul_f32_e32 v97, 0x45800000, v96
	v_cndmask_b32_e32 v96, v96, v97, vcc
	v_mul_f32_e32 v99, 0xbfb8aa3b, v96
	v_mul_f32_e32 v102, v99, v84
	v_mul_f32_e32 v103, v99, v85
	v_exp_f32_e32 v102, v102
	v_exp_f32_e32 v103, v103
	v_mul_f32_e32 v104, v99, v86
; template <int K, int EPI, bool MIX = false>
; __device__ __forceinline__ void gemm_phase(const Params& p, const u16* __restrict__ A, const u16* __restrict__ Bt,
;                            const float* __restrict__ rs_in, float* __restrict__ ssq_out, float alpha, bool rev = false) {
;     ...
;     if constexpr (EPI == EPI_SWIGLU) {
; #pragma unroll
;       for (int ai = 0; ai < 2; ++ai)
; #pragma unroll
;         for (int m = 0; m < 4; ++m) {
;           int row = brow + ai * 128 + wr * 64 + m * 16 + fr_e;
;           const float rs = rsqrtf(rsq[ai][m] * (1.f / DM) + 1e-6f);
;           const float c1 = rs * -1.4426950408889634f, rs2 = rs * rs;
;           u16* orow = p.Bbuf + blk_off(row, cpn * 128 + wc * 32, DFF) + wn16;
;           uint2 o2[2];
; #pragma unroll
;           for (int n = 0; n < 2; ++n) {
;             f32x4 g = acc[ai][0][m][n], u = acc[ai][1][m][n];
;             float h[4];
; #pragma unroll
;             for (int j = 0; j < 4; ++j) h[j] = (g[j] * u[j]) * (rs2 * __builtin_amdgcn_rcpf(1.f + __builtin_amdgcn_exp2f(g[j] * c1)));
;             o2[n].x = pk2(h[0], h[1]); o2[n].y = pk2(h[2], h[3]);
;           }
;           *(uint4*)orow = widen_pair(o2[0], o2[1]);
;         }
	v_mul_f32_e32 v105, v99, v87
	v_exp_f32_e32 v104, v104
	v_exp_f32_e32 v105, v105
	v_add_f32_e32 v102, 1.0, v102
	v_add_f32_e32 v103, 1.0, v103
	v_rcp_f32_e32 v102, v102
	v_rcp_f32_e32 v103, v103
	v_pk_mul_f32 v[86:87], v[86:87], v[94:95]
	v_add_f32_e32 v94, 1.0, v104
	v_add_f32_e32 v95, 1.0, v105
	v_rcp_f32_e32 v94, v94
	v_rcp_f32_e32 v95, v95
	v_mul_f32_e32 v98, v96, v96
	v_pk_mul_f32 v[84:85], v[84:85], v[92:93]
	v_pk_mul_f32 v[92:93], v[98:99], v[102:103] op_sel_hi:[0,1]
	v_pk_mul_f32 v[84:85], v[92:93], v[84:85]
	v_pk_mul_f32 v[92:93], v[98:99], v[94:95] op_sel_hi:[0,1]
	v_cvt_pk_bf16_f32 v84, v84, v85
	v_mul_f32_e32 v85, v99, v80
	v_pk_mul_f32 v[86:87], v[92:93], v[86:87]
	v_exp_f32_e32 v92, v85
	v_mul_f32_e32 v85, v99, v81
	v_exp_f32_e32 v93, v85
	v_cvt_pk_bf16_f32 v85, v86, v87
	v_add_f32_e32 v86, 1.0, v92
	v_mul_f32_e32 v92, v99, v82
	v_add_f32_e32 v87, 1.0, v93
	v_mul_f32_e32 v93, v99, v83
	v_exp_f32_e32 v92, v92
	v_exp_f32_e32 v93, v93
	v_rcp_f32_e32 v86, v86
	v_rcp_f32_e32 v87, v87
	v_pk_mul_f32 v[82:83], v[82:83], v[90:91]
	v_add_f32_e32 v90, 1.0, v92
	v_add_f32_e32 v91, 1.0, v93
	v_rcp_f32_e32 v90, v90
	v_rcp_f32_e32 v91, v91
	v_pk_mul_f32 v[80:81], v[80:81], v[88:89]
	v_pk_mul_f32 v[86:87], v[98:99], v[86:87] op_sel_hi:[0,1]
	v_pk_mul_f32 v[80:81], v[86:87], v[80:81]
	v_pk_mul_f32 v[86:87], v[98:99], v[90:91] op_sel_hi:[0,1]
	v_pk_mul_f32 v[82:83], v[86:87], v[82:83]
	v_or_b32_e32 v96, 0x1000, v214
	v_cvt_pk_bf16_f32 v87, v82, v83
	v_fmamk_f32 v82, v241, 0x3a000000, v236
	v_mul_f32_e32 v83, 0x4b800000, v82
	v_cmp_gt_f32_e32 vcc, s74, v82
	v_mov_b32_e32 v97, v215
	v_lshl_add_u64 v[100:101], s[52:53], 0, v[96:97]
	v_cndmask_b32_e32 v82, v82, v83, vcc
	v_rsq_f32_e32 v82, v82
	v_lshl_add_u64 v[100:101], v[100:101], 0, s[22:23]
	v_cvt_pk_bf16_f32 v86, v80, v81
	v_lshl_add_u64 v[80:81], v[100:101], 0, v[112:113]
	s_nop 0
	v_permlane32_swap_b32_e32 v84, v86
	v_permlane32_swap_b32_e32 v85, v87
	global_store_dwordx4 v[80:81], v[84:87], off sc0 sc1
	v_mul_f32_e32 v80, 0x45800000, v82
	v_cndmask_b32_e32 v80, v82, v80, vcc
	v_mul_f32_e32 v83, 0xbfb8aa3b, v80
	v_mul_f32_e32 v86, v83, v68
	v_mul_f32_e32 v87, v83, v69
	v_exp_f32_e32 v86, v86
	v_exp_f32_e32 v87, v87
	v_mul_f32_e32 v88, v83, v70
	v_mul_f32_e32 v89, v83, v71
	v_exp_f32_e32 v88, v88
	v_exp_f32_e32 v89, v89
	v_add_f32_e32 v86, 1.0, v86
	v_add_f32_e32 v87, 1.0, v87
	v_rcp_f32_e32 v86, v86
	v_rcp_f32_e32 v87, v87
	v_pk_mul_f32 v[70:71], v[70:71], v[78:79]
	v_add_f32_e32 v78, 1.0, v88
	v_add_f32_e32 v79, 1.0, v89
	v_rcp_f32_e32 v78, v78
	v_rcp_f32_e32 v79, v79
	v_mul_f32_e32 v82, v80, v80
	v_pk_mul_f32 v[68:69], v[68:69], v[76:77]
	v_pk_mul_f32 v[76:77], v[82:83], v[86:87] op_sel_hi:[0,1]
	v_pk_mul_f32 v[68:69], v[76:77], v[68:69]
	v_pk_mul_f32 v[76:77], v[82:83], v[78:79] op_sel_hi:[0,1]
	v_cvt_pk_bf16_f32 v68, v68, v69
	v_mul_f32_e32 v69, v83, v60
	v_pk_mul_f32 v[70:71], v[76:77], v[70:71]
	v_exp_f32_e32 v76, v69
	v_mul_f32_e32 v69, v83, v61
	v_exp_f32_e32 v77, v69
	v_cvt_pk_bf16_f32 v69, v70, v71
	v_add_f32_e32 v70, 1.0, v76
	v_mul_f32_e32 v76, v83, v62
	v_add_f32_e32 v71, 1.0, v77
	v_mul_f32_e32 v77, v83, v63
	v_exp_f32_e32 v76, v76
	v_exp_f32_e32 v77, v77
	v_rcp_f32_e32 v70, v70
	v_rcp_f32_e32 v71, v71
	v_pk_mul_f32 v[62:63], v[62:63], v[74:75]
	v_add_f32_e32 v74, 1.0, v76
	v_add_f32_e32 v75, 1.0, v77
	v_rcp_f32_e32 v74, v74
	v_rcp_f32_e32 v75, v75
	v_pk_mul_f32 v[60:61], v[60:61], v[72:73]
	v_pk_mul_f32 v[70:71], v[82:83], v[70:71] op_sel_hi:[0,1]
	v_or_b32_e32 v80, 0x1800, v214
	v_mov_b32_e32 v81, v215
	v_pk_mul_f32 v[60:61], v[70:71], v[60:61]
	v_pk_mul_f32 v[70:71], v[82:83], v[74:75] op_sel_hi:[0,1]
	v_lshl_add_u64 v[84:85], s[52:53], 0, v[80:81]
	v_pk_mul_f32 v[62:63], v[70:71], v[62:63]
	v_lshl_add_u64 v[84:85], v[84:85], 0, s[22:23]
	v_cvt_pk_bf16_f32 v70, v60, v61
	v_cvt_pk_bf16_f32 v71, v62, v63
	v_lshl_add_u64 v[60:61], v[84:85], 0, v[112:113]
	v_permlane32_swap_b32_e32 v68, v70
	v_permlane32_swap_b32_e32 v69, v71
	global_store_dwordx4 v[60:61], v[68:71], off sc0 sc1
	v_fmamk_f32 v60, v240, 0x3a000000, v236
	v_mul_f32_e32 v61, 0x4b800000, v60
	v_cmp_gt_f32_e32 vcc, s74, v60
	s_ashr_i32 s52, s59, 7
	s_mulk_i32 s52, 0x58
	v_cndmask_b32_e32 v60, v60, v61, vcc
	v_rsq_f32_e32 v60, v60
	s_ashr_i32 s53, s52, 31
	s_add_u32 s52, s52, s76
	s_addc_u32 s53, s53, s77
	v_mul_f32_e32 v61, 0x45800000, v60
	v_cndmask_b32_e32 v60, v60, v61, vcc
	v_mul_f32_e32 v61, 0xbfb8aa3b, v60
	v_mul_f32_e32 v68, v61, v56
	v_mul_f32_e32 v69, v61, v57
	v_exp_f32_e32 v68, v68
	v_exp_f32_e32 v69, v69
	v_mul_f32_e32 v70, v61, v58
	v_mul_f32_e32 v71, v61, v59
	v_exp_f32_e32 v70, v70
	v_exp_f32_e32 v71, v71
	v_add_f32_e32 v68, 1.0, v68
	v_add_f32_e32 v69, 1.0, v69
	v_rcp_f32_e32 v68, v68
	v_rcp_f32_e32 v69, v69
	v_pk_mul_f32 v[58:59], v[58:59], v[66:67]
	v_add_f32_e32 v66, 1.0, v70
	v_add_f32_e32 v67, 1.0, v71
	v_rcp_f32_e32 v66, v66
	v_rcp_f32_e32 v67, v67
	v_mul_f32_e32 v60, v60, v60
	v_pk_mul_f32 v[56:57], v[56:57], v[64:65]
	v_pk_mul_f32 v[64:65], v[60:61], v[68:69] op_sel_hi:[0,1]
	v_pk_mul_f32 v[56:57], v[64:65], v[56:57]
	v_pk_mul_f32 v[64:65], v[60:61], v[66:67] op_sel_hi:[0,1]
	v_cvt_pk_bf16_f32 v56, v56, v57
	v_mul_f32_e32 v57, v61, v48
	v_pk_mul_f32 v[58:59], v[64:65], v[58:59]
	v_exp_f32_e32 v64, v57
	v_mul_f32_e32 v57, v61, v49
	v_exp_f32_e32 v65, v57
	v_cvt_pk_bf16_f32 v57, v58, v59
	v_add_f32_e32 v58, 1.0, v64
	v_mul_f32_e32 v64, v61, v50
	v_mul_f32_e32 v61, v61, v51
	v_exp_f32_e32 v64, v64
	v_exp_f32_e32 v61, v61
	v_add_f32_e32 v59, 1.0, v65
	v_rcp_f32_e32 v58, v58
	v_rcp_f32_e32 v59, v59
	v_pk_mul_f32 v[50:51], v[50:51], v[54:55]
	v_add_f32_e32 v54, 1.0, v64
	v_add_f32_e32 v55, 1.0, v61
; template <int K, int EPI, bool MIX = false>
; __device__ __forceinline__ void gemm_phase(const Params& p, const u16* __restrict__ A, const u16* __restrict__ Bt,
;                            const float* __restrict__ rs_in, float* __restrict__ ssq_out, float alpha, bool rev = false) {
;     ...
;     if constexpr (EPI == EPI_SWIGLU) {
; #pragma unroll
;       for (int ai = 0; ai < 2; ++ai)
; #pragma unroll
;         for (int m = 0; m < 4; ++m) {
;           int row = brow + ai * 128 + wr * 64 + m * 16 + fr_e;
;           const float rs = rsqrtf(rsq[ai][m] * (1.f / DM) + 1e-6f);
;           const float c1 = rs * -1.4426950408889634f, rs2 = rs * rs;
;           u16* orow = p.Bbuf + blk_off(row, cpn * 128 + wc * 32, DFF) + wn16;
;           uint2 o2[2];
; #pragma unroll
;           for (int n = 0; n < 2; ++n) {
;             f32x4 g = acc[ai][0][m][n], u = acc[ai][1][m][n];
;             float h[4];
; #pragma unroll
;             for (int j = 0; j < 4; ++j) h[j] = (g[j] * u[j]) * (rs2 * __builtin_amdgcn_rcpf(1.f + __builtin_amdgcn_exp2f(g[j] * c1)));
;             o2[n].x = pk2(h[0], h[1]); o2[n].y = pk2(h[2], h[3]);
;           }
;           *(uint4*)orow = widen_pair(o2[0], o2[1]);
;         }
	v_rcp_f32_e32 v54, v54
	v_rcp_f32_e32 v55, v55
	v_pk_mul_f32 v[48:49], v[48:49], v[52:53]
	v_pk_mul_f32 v[52:53], v[60:61], v[58:59] op_sel_hi:[0,1]
	v_pk_mul_f32 v[48:49], v[52:53], v[48:49]
	v_pk_mul_f32 v[52:53], v[60:61], v[54:55] op_sel_hi:[0,1]
	v_pk_mul_f32 v[50:51], v[52:53], v[50:51]
	s_lshl_b64 s[52:53], s[52:53], 14
	v_cvt_pk_bf16_f32 v59, v50, v51
	v_fmamk_f32 v50, v239, 0x3a000000, v236
	v_mul_f32_e32 v51, 0x4b800000, v50
	v_cmp_gt_f32_e32 vcc, s74, v50
	s_add_u32 s52, s92, s52
	s_addc_u32 s53, s93, s53
	v_cndmask_b32_e32 v50, v50, v51, vcc
	v_rsq_f32_e32 v50, v50
	v_lshl_add_u64 v[62:63], s[52:53], 0, v[214:215]
	v_lshl_add_u64 v[62:63], v[62:63], 0, s[22:23]
	v_cvt_pk_bf16_f32 v58, v48, v49
	v_mul_f32_e32 v51, 0x45800000, v50
	v_cndmask_b32_e32 v50, v50, v51, vcc
	v_mul_f32_e32 v51, 0xbfb8aa3b, v50
	v_mul_f32_e32 v52, v51, v40
	v_mul_f32_e32 v53, v51, v41
	v_exp_f32_e32 v52, v52
	v_exp_f32_e32 v53, v53
	v_mul_f32_e32 v54, v51, v42
	v_mul_f32_e32 v55, v51, v43
	v_exp_f32_e32 v54, v54
	v_exp_f32_e32 v55, v55
	v_add_f32_e32 v52, 1.0, v52
	v_add_f32_e32 v53, 1.0, v53
	v_rcp_f32_e32 v52, v52
	v_rcp_f32_e32 v53, v53
	v_pk_mul_f32 v[42:43], v[42:43], v[46:47]
	v_add_f32_e32 v46, 1.0, v54
	v_add_f32_e32 v47, 1.0, v55
	v_rcp_f32_e32 v46, v46
	v_rcp_f32_e32 v47, v47
	v_mul_f32_e32 v50, v50, v50
	v_pk_mul_f32 v[40:41], v[40:41], v[44:45]
	v_pk_mul_f32 v[44:45], v[50:51], v[52:53] op_sel_hi:[0,1]
	v_pk_mul_f32 v[40:41], v[44:45], v[40:41]
	v_pk_mul_f32 v[44:45], v[50:51], v[46:47] op_sel_hi:[0,1]
	v_cvt_pk_bf16_f32 v40, v40, v41
	v_mul_f32_e32 v41, v51, v32
	v_pk_mul_f32 v[42:43], v[44:45], v[42:43]
	v_exp_f32_e32 v44, v41
	v_mul_f32_e32 v41, v51, v33
	v_exp_f32_e32 v45, v41
	v_cvt_pk_bf16_f32 v41, v42, v43
	v_add_f32_e32 v42, 1.0, v44
	v_rcp_f32_e32 v42, v42
	v_add_f32_e32 v43, 1.0, v45
	v_rcp_f32_e32 v43, v43
	v_pk_mul_f32 v[32:33], v[32:33], v[36:37]
	v_mul_f32_e32 v44, v51, v34
	v_mul_f32_e32 v45, v51, v35
	v_pk_mul_f32 v[36:37], v[50:51], v[42:43] op_sel_hi:[0,1]
	v_pk_mul_f32 v[32:33], v[36:37], v[32:33]
	v_exp_f32_e32 v44, v44
	v_exp_f32_e32 v45, v45
	v_cvt_pk_bf16_f32 v42, v32, v33
	v_fmamk_f32 v32, v238, 0x3a000000, v236
	v_mul_f32_e32 v33, 0x4b800000, v32
	v_cmp_gt_f32_e32 vcc, s74, v32
	v_pk_mul_f32 v[34:35], v[34:35], v[38:39]
	v_add_f32_e32 v38, 1.0, v44
	v_cndmask_b32_e32 v32, v32, v33, vcc
	v_rsq_f32_e32 v32, v32
	v_add_f32_e32 v39, 1.0, v45
	v_rcp_f32_e32 v38, v38
	v_rcp_f32_e32 v39, v39
	v_mul_f32_e32 v33, 0x45800000, v32
	v_cndmask_b32_e32 v32, v32, v33, vcc
	v_mul_f32_e32 v33, 0xbfb8aa3b, v32
	v_pk_mul_f32 v[36:37], v[50:51], v[38:39] op_sel_hi:[0,1]
	v_pk_mul_f32 v[34:35], v[36:37], v[34:35]
	v_mul_f32_e32 v36, v33, v24
	v_mul_f32_e32 v37, v33, v25
	v_exp_f32_e32 v36, v36
	v_exp_f32_e32 v37, v37
	v_mul_f32_e32 v38, v33, v26
	v_mul_f32_e32 v39, v33, v27
	v_exp_f32_e32 v38, v38
	v_exp_f32_e32 v39, v39
	v_add_f32_e32 v36, 1.0, v36
	v_add_f32_e32 v37, 1.0, v37
	v_rcp_f32_e32 v36, v36
	v_rcp_f32_e32 v37, v37
	v_pk_mul_f32 v[26:27], v[26:27], v[30:31]
	v_add_f32_e32 v30, 1.0, v38
	v_add_f32_e32 v31, 1.0, v39
	v_rcp_f32_e32 v30, v30
	v_rcp_f32_e32 v31, v31
	v_mul_f32_e32 v32, v32, v32
	v_pk_mul_f32 v[24:25], v[24:25], v[28:29]
	v_pk_mul_f32 v[28:29], v[32:33], v[36:37] op_sel_hi:[0,1]
	v_pk_mul_f32 v[24:25], v[28:29], v[24:25]
	v_pk_mul_f32 v[28:29], v[32:33], v[30:31] op_sel_hi:[0,1]
	v_cvt_pk_bf16_f32 v24, v24, v25
	v_mul_f32_e32 v25, v33, v16
	v_pk_mul_f32 v[26:27], v[28:29], v[26:27]
	v_exp_f32_e32 v28, v25
	v_mul_f32_e32 v25, v33, v17
	v_exp_f32_e32 v29, v25
	v_cvt_pk_bf16_f32 v25, v26, v27
	v_add_f32_e32 v26, 1.0, v28
	v_mul_f32_e32 v28, v33, v18
	v_add_f32_e32 v27, 1.0, v29
	v_mul_f32_e32 v29, v33, v19
	v_exp_f32_e32 v28, v28
	v_exp_f32_e32 v29, v29
	v_rcp_f32_e32 v26, v26
	v_rcp_f32_e32 v27, v27
	v_pk_mul_f32 v[18:19], v[18:19], v[22:23]
	v_add_f32_e32 v22, 1.0, v28
	v_add_f32_e32 v23, 1.0, v29
	v_rcp_f32_e32 v22, v22
	v_rcp_f32_e32 v23, v23
	v_pk_mul_f32 v[16:17], v[16:17], v[20:21]
	v_pk_mul_f32 v[20:21], v[32:33], v[26:27] op_sel_hi:[0,1]
	v_pk_mul_f32 v[16:17], v[20:21], v[16:17]
	v_pk_mul_f32 v[20:21], v[32:33], v[22:23] op_sel_hi:[0,1]
	v_pk_mul_f32 v[18:19], v[20:21], v[18:19]
	v_cvt_pk_bf16_f32 v43, v34, v35
	v_cvt_pk_bf16_f32 v27, v18, v19
	v_fmamk_f32 v18, v237, 0x3a000000, v236
	v_mul_f32_e32 v19, 0x4b800000, v18
	v_cmp_gt_f32_e32 vcc, s74, v18
	v_lshl_add_u64 v[34:35], s[52:53], 0, v[96:97]
	v_lshl_add_u64 v[34:35], v[34:35], 0, s[22:23]
	v_cndmask_b32_e32 v18, v18, v19, vcc
	v_rsq_f32_e32 v18, v18
	v_cvt_pk_bf16_f32 v26, v16, v17
	v_lshl_add_u64 v[16:17], v[34:35], 0, v[112:113]
	s_nop 0
	v_permlane32_swap_b32_e32 v24, v26
	v_permlane32_swap_b32_e32 v25, v27
	global_store_dwordx4 v[16:17], v[24:27], off sc0 sc1
	v_mul_f32_e32 v16, 0x45800000, v18
	v_cndmask_b32_e32 v16, v18, v16, vcc
	v_mul_f32_e32 v17, 0xbfb8aa3b, v16
	v_mul_f32_e32 v20, v17, v8
	v_mul_f32_e32 v21, v17, v9
	v_exp_f32_e32 v20, v20
	v_exp_f32_e32 v21, v21
	v_mul_f32_e32 v22, v17, v10
	v_mul_f32_e32 v23, v17, v11
	v_exp_f32_e32 v22, v22
	v_exp_f32_e32 v23, v23
	v_add_f32_e32 v20, 1.0, v20
	v_add_f32_e32 v21, 1.0, v21
	v_rcp_f32_e32 v20, v20
	v_rcp_f32_e32 v21, v21
	v_pk_mul_f32 v[10:11], v[10:11], v[14:15]
	v_add_f32_e32 v14, 1.0, v22
	v_add_f32_e32 v15, 1.0, v23
	v_rcp_f32_e32 v14, v14
	v_rcp_f32_e32 v15, v15
	v_mul_f32_e32 v16, v16, v16
	v_pk_mul_f32 v[8:9], v[8:9], v[12:13]
	v_pk_mul_f32 v[12:13], v[16:17], v[20:21] op_sel_hi:[0,1]
	v_pk_mul_f32 v[8:9], v[12:13], v[8:9]
	v_pk_mul_f32 v[12:13], v[16:17], v[14:15] op_sel_hi:[0,1]
	v_cvt_pk_bf16_f32 v8, v8, v9
	v_mul_f32_e32 v9, v17, v0
	v_pk_mul_f32 v[10:11], v[12:13], v[10:11]
	v_exp_f32_e32 v12, v9
	v_mul_f32_e32 v9, v17, v1
	v_exp_f32_e32 v13, v9
	v_cvt_pk_bf16_f32 v9, v10, v11
	v_add_f32_e32 v10, 1.0, v12
	v_mul_f32_e32 v12, v17, v2
	v_add_f32_e32 v11, 1.0, v13
	v_mul_f32_e32 v13, v17, v3
	v_exp_f32_e32 v12, v12
	v_exp_f32_e32 v13, v13
	v_rcp_f32_e32 v10, v10
	v_rcp_f32_e32 v11, v11
	v_pk_mul_f32 v[2:3], v[2:3], v[6:7]
	v_add_f32_e32 v6, 1.0, v12
	v_add_f32_e32 v7, 1.0, v13
	v_rcp_f32_e32 v6, v6
	v_rcp_f32_e32 v7, v7
	v_pk_mul_f32 v[0:1], v[0:1], v[4:5]
	v_pk_mul_f32 v[4:5], v[16:17], v[10:11] op_sel_hi:[0,1]
	v_pk_mul_f32 v[0:1], v[4:5], v[0:1]
	v_pk_mul_f32 v[4:5], v[16:17], v[6:7] op_sel_hi:[0,1]
	v_lshl_add_u64 v[18:19], s[52:53], 0, v[80:81]
	v_pk_mul_f32 v[2:3], v[4:5], v[2:3]
	v_lshl_add_u64 v[18:19], v[18:19], 0, s[22:23]
	v_cvt_pk_bf16_f32 v10, v0, v1
	v_cvt_pk_bf16_f32 v11, v2, v3
	v_lshl_add_u64 v[48:49], v[62:63], 0, v[112:113]
	v_permlane32_swap_b32_e32 v56, v58
	v_permlane32_swap_b32_e32 v57, v59
	v_permlane32_swap_b32_e32 v40, v42
	v_permlane32_swap_b32_e32 v41, v43
	v_lshl_add_u64 v[0:1], v[18:19], 0, v[112:113]
	v_permlane32_swap_b32_e32 v8, v10
	v_permlane32_swap_b32_e32 v9, v11
	s_and_b64 vcc, exec, s[4:5]
	s_mov_b64 s[4:5], -1
	global_store_dwordx4 v[48:49], v[56:59], off sc0 sc1
	global_store_dwordx4 v[48:49], v[40:43], off offset:2048 sc0 sc1
	global_store_dwordx4 v[0:1], v[8:11], off sc0 sc1
	s_cbranch_vccnz .LBB0_421
; #define SCHED __builtin_amdgcn_sched_barrier(0)
; template <int K, int EPI, bool MIX = false>
; __device__ __forceinline__ void gemm_phase(const Params& p, const u16* __restrict__ A, const u16* __restrict__ Bt,
;                            const float* __restrict__ rs_in, float* __restrict__ ssq_out, float alpha, bool rev = false) {
;     ...
;     if (!more) break;
;     asm volatile("" ::: "memory");
;     SCHED;
;   }
	s_mov_b64 s[4:5], 0
	s_branch .LBB0_421
